# compress MLP2 loop: weights prefetched one iteration ahead, LDS reads double-buffered
# speedup vs baseline: 1.0974x; 1.0021x over previous
; DI float siluf_(float x) { return x / (1.f + __expf(-x)); }
; DI void compress_item(const Params& p, int l, int item, char* lds) {
;     ...
;   const float* w2 = (kv ? p.cmp_v_w2 : p.cmp_k_w2) + (size_t)l * 128 * 64;
;     ...
;   float* hid = (float*)lds;
; #pragma unroll
;   for (int mi = 0; mi < 2; ++mi)
; #pragma unroll
;     for (int ni = 0; ni < 2; ++ni)
; #pragma unroll
;       for (int i = 0; i < 16; ++i) {
;         const int row = wm * 64 + mi * 32 + r, col = wn * 64 + ni * 32 + (i & 3) + 8 * (i >> 2) + 4 * h;
;         hid[row * 132 + col] = siluf_(acc[mi][ni][i] + pw[ni][i]);
;       }
.LBB0_427:
	v_pk_add_f32 v[50:51], v[94:95], v[50:51]
	v_and_b32_e32 v0, 31, v162
	v_mul_f32_e32 v98, 0xbfb8aa3b, v50
	v_mul_f32_e32 v99, 0xbfb8aa3b, v51
	v_exp_f32_e32 v98, v98
	v_exp_f32_e32 v99, v99
	v_and_or_b32 v0, v178, s74, v0
	s_movk_i32 s14, 0x210
	v_mul_lo_u32 v0, v0, s14
	v_pk_add_f32 v[98:99], v[98:99], 1.0 op_sel_hi:[1,0]
	v_pk_add_f32 v[52:53], v[96:97], v[52:53]
	v_div_scale_f32 v100, s[14:15], v99, v99, v51
	v_rcp_f32_e32 v101, v100
	v_add3_u32 v0, v176, v0, v177
	v_pk_add_f32 v[34:35], v[78:79], v[34:35]
	v_pk_add_f32 v[36:37], v[80:81], v[36:37]
	v_fma_f32 v102, -v100, v101, 1.0
	v_fmac_f32_e32 v101, v102, v101
	v_div_scale_f32 v102, vcc, v51, v99, v51
	v_mul_f32_e32 v103, v102, v101
	v_fma_f32 v104, -v100, v103, v102
	v_fmac_f32_e32 v103, v104, v101
	v_fma_f32 v100, -v100, v103, v102
	v_div_fmas_f32 v100, v100, v101, v103
	v_div_fixup_f32 v51, v100, v99, v51
	v_div_scale_f32 v99, s[14:15], v98, v98, v50
	v_rcp_f32_e32 v100, v99
	v_pk_add_f32 v[18:19], v[94:95], v[18:19]
	v_pk_add_f32 v[20:21], v[96:97], v[20:21]
	v_pk_add_f32 v[2:3], v[78:79], v[2:3]
	v_fma_f32 v101, -v99, v100, 1.0
	v_fmac_f32_e32 v100, v101, v100
	v_div_scale_f32 v101, vcc, v50, v98, v50
	v_mul_f32_e32 v102, v101, v100
	v_fma_f32 v103, -v99, v102, v101
	v_fmac_f32_e32 v102, v103, v100
	v_fma_f32 v99, -v99, v102, v101
	v_div_fmas_f32 v99, v99, v100, v102
	v_div_fixup_f32 v50, v99, v98, v50
	v_mul_f32_e32 v98, 0xbfb8aa3b, v52
	v_mul_f32_e32 v99, 0xbfb8aa3b, v53
	v_exp_f32_e32 v98, v98
	v_exp_f32_e32 v99, v99
	v_pk_add_f32 v[4:5], v[80:81], v[4:5]
	v_readlane_b32 s80, v251, 18
	s_and_b64 s[12:13], s[0:1], exec
	v_pk_add_f32 v[98:99], v[98:99], 1.0 op_sel_hi:[1,0]
	v_readlane_b32 s82, v251, 20
	v_div_scale_f32 v100, s[14:15], v99, v99, v53
	v_rcp_f32_e32 v101, v100
	v_readlane_b32 s86, v251, 24
	v_readlane_b32 s83, v251, 21
	v_readlane_b32 s87, v251, 25
	v_fma_f32 v102, -v100, v101, 1.0
	v_fmac_f32_e32 v101, v102, v101
	v_div_scale_f32 v102, vcc, v53, v99, v53
	v_mul_f32_e32 v103, v102, v101
	v_fma_f32 v104, -v100, v103, v102
	v_fmac_f32_e32 v103, v104, v101
	v_fma_f32 v100, -v100, v103, v102
	v_div_fmas_f32 v100, v100, v101, v103
	v_div_fixup_f32 v53, v100, v99, v53
	v_div_scale_f32 v99, s[14:15], v98, v98, v52
	v_rcp_f32_e32 v100, v99
	s_cselect_b32 s13, s82, s86
	s_cselect_b32 s12, s83, s87
	v_readlane_b32 s81, v251, 19
	v_fma_f32 v101, -v99, v100, 1.0
	v_fmac_f32_e32 v100, v101, v100
	v_div_scale_f32 v101, vcc, v52, v98, v52
	v_mul_f32_e32 v102, v101, v100
	v_fma_f32 v103, -v99, v102, v101
	v_fmac_f32_e32 v102, v103, v100
	v_fma_f32 v99, -v99, v102, v101
	v_div_fmas_f32 v99, v99, v100, v102
	v_div_fixup_f32 v52, v99, v98, v52
	ds_write_b128 v0, v[50:53]
	v_pk_add_f32 v[50:51], v[90:91], v[54:55]
	v_readlane_b32 s84, v251, 22
	v_mul_f32_e32 v52, 0xbfb8aa3b, v50
	v_mul_f32_e32 v53, 0xbfb8aa3b, v51
	v_exp_f32_e32 v52, v52
	v_exp_f32_e32 v53, v53
	v_readlane_b32 s85, v251, 23
	v_readlane_b32 s88, v251, 26
	v_readlane_b32 s89, v251, 27
	v_pk_add_f32 v[52:53], v[52:53], 1.0 op_sel_hi:[1,0]
	v_readlane_b32 s90, v251, 28
	v_div_scale_f32 v54, s[14:15], v53, v53, v51
	v_rcp_f32_e32 v55, v54
	v_readlane_b32 s91, v251, 29
	v_readlane_b32 s92, v251, 30
	v_readlane_b32 s93, v251, 31
	v_fma_f32 v98, -v54, v55, 1.0
	v_fmac_f32_e32 v55, v98, v55
	v_div_scale_f32 v98, vcc, v51, v53, v51
	v_mul_f32_e32 v99, v98, v55
	v_fma_f32 v100, -v54, v99, v98
	v_fmac_f32_e32 v99, v100, v55
	v_fma_f32 v54, -v54, v99, v98
	v_div_fmas_f32 v54, v54, v55, v99
	v_div_fixup_f32 v51, v54, v53, v51
	v_div_scale_f32 v53, s[14:15], v52, v52, v50
	v_rcp_f32_e32 v54, v53
	v_readlane_b32 s94, v251, 32
	v_readlane_b32 s95, v251, 33
	v_fma_f32 v55, -v53, v54, 1.0
	v_fmac_f32_e32 v54, v55, v54
	v_div_scale_f32 v55, vcc, v50, v52, v50
	v_mul_f32_e32 v98, v55, v54
	v_fma_f32 v99, -v53, v98, v55
	v_fmac_f32_e32 v98, v99, v54
	v_fma_f32 v53, -v53, v98, v55
	v_div_fmas_f32 v53, v53, v54, v98
	v_div_fixup_f32 v50, v53, v52, v50
	v_pk_add_f32 v[52:53], v[92:93], v[56:57]
	s_nop 0
	v_mul_f32_e32 v54, 0xbfb8aa3b, v52
	v_mul_f32_e32 v55, 0xbfb8aa3b, v53
	v_exp_f32_e32 v54, v54
	v_exp_f32_e32 v55, v55
	s_nop 0
	v_pk_add_f32 v[54:55], v[54:55], 1.0 op_sel_hi:[1,0]
	s_nop 0
	v_div_scale_f32 v56, s[14:15], v55, v55, v53
	v_rcp_f32_e32 v57, v56
	s_nop 0
	v_fma_f32 v98, -v56, v57, 1.0
	v_fmac_f32_e32 v57, v98, v57
	v_div_scale_f32 v98, vcc, v53, v55, v53
	v_mul_f32_e32 v99, v98, v57
	v_fma_f32 v100, -v56, v99, v98
	v_fmac_f32_e32 v99, v100, v57
	v_fma_f32 v56, -v56, v99, v98
	v_div_fmas_f32 v56, v56, v57, v99
	v_div_fixup_f32 v53, v56, v55, v53
	v_div_scale_f32 v55, s[14:15], v54, v54, v52
	v_rcp_f32_e32 v56, v55
	s_nop 0
	v_fma_f32 v57, -v55, v56, 1.0
	v_fmac_f32_e32 v56, v57, v56
	v_div_scale_f32 v57, vcc, v52, v54, v52
	v_mul_f32_e32 v98, v57, v56
	v_fma_f32 v99, -v55, v98, v57
	v_fmac_f32_e32 v98, v99, v56
	v_fma_f32 v55, -v55, v98, v57
	v_div_fmas_f32 v55, v55, v56, v98
	v_div_fixup_f32 v52, v55, v54, v52
	ds_write_b128 v0, v[50:53] offset:32
	v_pk_add_f32 v[50:51], v[86:87], v[58:59]
	s_nop 0
	v_mul_f32_e32 v52, 0xbfb8aa3b, v50
	v_mul_f32_e32 v53, 0xbfb8aa3b, v51
	v_exp_f32_e32 v52, v52
	v_exp_f32_e32 v53, v53
	s_nop 0
	v_pk_add_f32 v[52:53], v[52:53], 1.0 op_sel_hi:[1,0]
	s_nop 0
	v_div_scale_f32 v54, s[14:15], v53, v53, v51
	v_rcp_f32_e32 v55, v54
	s_nop 0
	v_fma_f32 v56, -v54, v55, 1.0
	v_fmac_f32_e32 v55, v56, v55
	v_div_scale_f32 v56, vcc, v51, v53, v51
	v_mul_f32_e32 v57, v56, v55
	v_fma_f32 v58, -v54, v57, v56
	v_fmac_f32_e32 v57, v58, v55
	v_fma_f32 v54, -v54, v57, v56
	v_div_fmas_f32 v54, v54, v55, v57
	v_div_fixup_f32 v51, v54, v53, v51
	v_div_scale_f32 v53, s[14:15], v52, v52, v50
; DI float siluf_(float x) { return x / (1.f + __expf(-x)); }
; DI void compress_item(const Params& p, int l, int item, char* lds) {
;     ...
;   float* hid = (float*)lds;
; #pragma unroll
;   for (int mi = 0; mi < 2; ++mi)
; #pragma unroll
;     for (int ni = 0; ni < 2; ++ni)
; #pragma unroll
;       for (int i = 0; i < 16; ++i) {
;         const int row = wm * 64 + mi * 32 + r, col = wn * 64 + ni * 32 + (i & 3) + 8 * (i >> 2) + 4 * h;
;         hid[row * 132 + col] = siluf_(acc[mi][ni][i] + pw[ni][i]);
;       }
	v_rcp_f32_e32 v54, v53
	s_nop 0
	v_fma_f32 v55, -v53, v54, 1.0
	v_fmac_f32_e32 v54, v55, v54
	v_div_scale_f32 v55, vcc, v50, v52, v50
	v_mul_f32_e32 v56, v55, v54
	v_fma_f32 v57, -v53, v56, v55
	v_fmac_f32_e32 v56, v57, v54
	v_fma_f32 v53, -v53, v56, v55
	v_div_fmas_f32 v53, v53, v54, v56
	v_div_fixup_f32 v50, v53, v52, v50
	v_pk_add_f32 v[52:53], v[88:89], v[60:61]
	s_nop 0
	v_mul_f32_e32 v54, 0xbfb8aa3b, v52
	v_mul_f32_e32 v55, 0xbfb8aa3b, v53
	v_exp_f32_e32 v54, v54
	v_exp_f32_e32 v55, v55
	s_nop 0
	v_pk_add_f32 v[54:55], v[54:55], 1.0 op_sel_hi:[1,0]
	s_nop 0
	v_div_scale_f32 v56, s[14:15], v55, v55, v53
	v_rcp_f32_e32 v57, v56
	s_nop 0
	v_fma_f32 v58, -v56, v57, 1.0
	v_fmac_f32_e32 v57, v58, v57
	v_div_scale_f32 v58, vcc, v53, v55, v53
	v_mul_f32_e32 v59, v58, v57
	v_fma_f32 v60, -v56, v59, v58
	v_fmac_f32_e32 v59, v60, v57
	v_fma_f32 v56, -v56, v59, v58
	v_div_fmas_f32 v56, v56, v57, v59
	v_div_fixup_f32 v53, v56, v55, v53
	v_div_scale_f32 v55, s[14:15], v54, v54, v52
	v_rcp_f32_e32 v56, v55
	s_nop 0
	v_fma_f32 v57, -v55, v56, 1.0
	v_fmac_f32_e32 v56, v57, v56
	v_div_scale_f32 v57, vcc, v52, v54, v52
	v_mul_f32_e32 v58, v57, v56
	v_fma_f32 v59, -v55, v58, v57
	v_fmac_f32_e32 v58, v59, v56
	v_fma_f32 v55, -v55, v58, v57
	v_div_fmas_f32 v55, v55, v56, v58
	v_div_fixup_f32 v52, v55, v54, v52
	ds_write_b128 v0, v[50:53] offset:64
	v_pk_add_f32 v[50:51], v[82:83], v[62:63]
	s_nop 0
	v_mul_f32_e32 v52, 0xbfb8aa3b, v50
	v_mul_f32_e32 v53, 0xbfb8aa3b, v51
	v_exp_f32_e32 v52, v52
	v_exp_f32_e32 v53, v53
	s_nop 0
	v_pk_add_f32 v[52:53], v[52:53], 1.0 op_sel_hi:[1,0]
	s_nop 0
	v_div_scale_f32 v54, s[14:15], v53, v53, v51
	v_rcp_f32_e32 v55, v54
	s_nop 0
	v_fma_f32 v56, -v54, v55, 1.0
	v_fmac_f32_e32 v55, v56, v55
	v_div_scale_f32 v56, vcc, v51, v53, v51
	v_mul_f32_e32 v57, v56, v55
	v_fma_f32 v58, -v54, v57, v56
	v_fmac_f32_e32 v57, v58, v55
	v_fma_f32 v54, -v54, v57, v56
	v_div_fmas_f32 v54, v54, v55, v57
	v_div_fixup_f32 v51, v54, v53, v51
	v_div_scale_f32 v53, s[14:15], v52, v52, v50
	v_rcp_f32_e32 v54, v53
	s_nop 0
	v_fma_f32 v55, -v53, v54, 1.0
	v_fmac_f32_e32 v54, v55, v54
	v_div_scale_f32 v55, vcc, v50, v52, v50
	v_mul_f32_e32 v56, v55, v54
	v_fma_f32 v57, -v53, v56, v55
	v_fmac_f32_e32 v56, v57, v54
	v_fma_f32 v53, -v53, v56, v55
	v_div_fmas_f32 v53, v53, v54, v56
	v_div_fixup_f32 v50, v53, v52, v50
	v_pk_add_f32 v[52:53], v[84:85], v[64:65]
	s_nop 0
	v_mul_f32_e32 v54, 0xbfb8aa3b, v52
	v_mul_f32_e32 v55, 0xbfb8aa3b, v53
	v_exp_f32_e32 v54, v54
	v_exp_f32_e32 v55, v55
	s_nop 0
	v_pk_add_f32 v[54:55], v[54:55], 1.0 op_sel_hi:[1,0]
	s_nop 0
	v_div_scale_f32 v56, s[14:15], v55, v55, v53
	v_rcp_f32_e32 v57, v56
	s_nop 0
	v_fma_f32 v58, -v56, v57, 1.0
	v_fmac_f32_e32 v57, v58, v57
	v_div_scale_f32 v58, vcc, v53, v55, v53
	v_mul_f32_e32 v59, v58, v57
	v_fma_f32 v60, -v56, v59, v58
	v_fmac_f32_e32 v59, v60, v57
	v_fma_f32 v56, -v56, v59, v58
	v_div_fmas_f32 v56, v56, v57, v59
	v_div_fixup_f32 v53, v56, v55, v53
	v_div_scale_f32 v55, s[14:15], v54, v54, v52
	v_rcp_f32_e32 v56, v55
	s_nop 0
	v_fma_f32 v57, -v55, v56, 1.0
	v_fmac_f32_e32 v56, v57, v56
	v_div_scale_f32 v57, vcc, v52, v54, v52
	v_mul_f32_e32 v58, v57, v56
	v_fma_f32 v59, -v55, v58, v57
	v_fmac_f32_e32 v58, v59, v56
	v_fma_f32 v55, -v55, v58, v57
	v_div_fmas_f32 v55, v55, v56, v58
	v_div_fixup_f32 v52, v55, v54, v52
	ds_write_b128 v0, v[50:53] offset:96
	v_mul_f32_e32 v50, 0xbfb8aa3b, v34
	v_mul_f32_e32 v51, 0xbfb8aa3b, v35
	v_exp_f32_e32 v50, v50
	v_exp_f32_e32 v51, v51
	s_nop 0
	v_pk_add_f32 v[50:51], v[50:51], 1.0 op_sel_hi:[1,0]
	s_nop 0
	v_div_scale_f32 v52, s[14:15], v51, v51, v35
	v_rcp_f32_e32 v53, v52
	s_nop 0
	v_fma_f32 v54, -v52, v53, 1.0
	v_fmac_f32_e32 v53, v54, v53
	v_div_scale_f32 v54, vcc, v35, v51, v35
	v_mul_f32_e32 v55, v54, v53
	v_fma_f32 v56, -v52, v55, v54
	v_fmac_f32_e32 v55, v56, v53
	v_fma_f32 v52, -v52, v55, v54
	v_div_fmas_f32 v52, v52, v53, v55
	v_div_fixup_f32 v35, v52, v51, v35
	v_div_scale_f32 v51, s[14:15], v50, v50, v34
	v_rcp_f32_e32 v52, v51
	s_nop 0
	v_fma_f32 v53, -v51, v52, 1.0
	v_fmac_f32_e32 v52, v53, v52
	v_div_scale_f32 v53, vcc, v34, v50, v34
	v_mul_f32_e32 v54, v53, v52
	v_fma_f32 v55, -v51, v54, v53
	v_fmac_f32_e32 v54, v55, v52
	v_fma_f32 v51, -v51, v54, v53
	v_div_fmas_f32 v51, v51, v52, v54
	v_div_fixup_f32 v34, v51, v50, v34
	v_mul_f32_e32 v50, 0xbfb8aa3b, v36
	v_mul_f32_e32 v51, 0xbfb8aa3b, v37
	v_exp_f32_e32 v50, v50
	v_exp_f32_e32 v51, v51
	s_nop 0
	v_pk_add_f32 v[50:51], v[50:51], 1.0 op_sel_hi:[1,0]
	s_nop 0
	v_div_scale_f32 v52, s[14:15], v51, v51, v37
	v_rcp_f32_e32 v53, v52
	s_nop 0
	v_fma_f32 v54, -v52, v53, 1.0
	v_fmac_f32_e32 v53, v54, v53
	v_div_scale_f32 v54, vcc, v37, v51, v37
	v_mul_f32_e32 v55, v54, v53
	v_fma_f32 v56, -v52, v55, v54
	v_fmac_f32_e32 v55, v56, v53
	v_fma_f32 v52, -v52, v55, v54
	v_div_fmas_f32 v52, v52, v53, v55
	v_div_fixup_f32 v37, v52, v51, v37
	v_div_scale_f32 v51, s[14:15], v50, v50, v36
	v_rcp_f32_e32 v52, v51
	s_nop 0
	v_fma_f32 v53, -v51, v52, 1.0
	v_fmac_f32_e32 v52, v53, v52
	v_div_scale_f32 v53, vcc, v36, v50, v36
	v_mul_f32_e32 v54, v53, v52
	v_fma_f32 v55, -v51, v54, v53
	v_fmac_f32_e32 v54, v55, v52
	v_fma_f32 v51, -v51, v54, v53
	v_div_fmas_f32 v51, v51, v52, v54
	v_div_fixup_f32 v36, v51, v50, v36
	ds_write_b128 v0, v[34:37] offset:128
	v_pk_add_f32 v[34:35], v[74:75], v[38:39]
	s_nop 0
	v_mul_f32_e32 v36, 0xbfb8aa3b, v34
	v_mul_f32_e32 v37, 0xbfb8aa3b, v35
	v_exp_f32_e32 v36, v36
	v_exp_f32_e32 v37, v37
	s_nop 0
	v_pk_add_f32 v[36:37], v[36:37], 1.0 op_sel_hi:[1,0]
	s_nop 0
	v_div_scale_f32 v38, s[14:15], v37, v37, v35
	v_rcp_f32_e32 v39, v38
	s_nop 0
	v_fma_f32 v50, -v38, v39, 1.0
; DI float siluf_(float x) { return x / (1.f + __expf(-x)); }
; DI void compress_item(const Params& p, int l, int item, char* lds) {
;     ...
;   float* hid = (float*)lds;
; #pragma unroll
;   for (int mi = 0; mi < 2; ++mi)
; #pragma unroll
;     for (int ni = 0; ni < 2; ++ni)
; #pragma unroll
;       for (int i = 0; i < 16; ++i) {
;         const int row = wm * 64 + mi * 32 + r, col = wn * 64 + ni * 32 + (i & 3) + 8 * (i >> 2) + 4 * h;
;         hid[row * 132 + col] = siluf_(acc[mi][ni][i] + pw[ni][i]);
;       }
	v_fmac_f32_e32 v39, v50, v39
	v_div_scale_f32 v50, vcc, v35, v37, v35
	v_mul_f32_e32 v51, v50, v39
	v_fma_f32 v52, -v38, v51, v50
	v_fmac_f32_e32 v51, v52, v39
	v_fma_f32 v38, -v38, v51, v50
	v_div_fmas_f32 v38, v38, v39, v51
	v_div_fixup_f32 v35, v38, v37, v35
	v_div_scale_f32 v37, s[14:15], v36, v36, v34
	v_rcp_f32_e32 v38, v37
	s_nop 0
	v_fma_f32 v39, -v37, v38, 1.0
	v_fmac_f32_e32 v38, v39, v38
	v_div_scale_f32 v39, vcc, v34, v36, v34
	v_mul_f32_e32 v50, v39, v38
	v_fma_f32 v51, -v37, v50, v39
	v_fmac_f32_e32 v50, v51, v38
	v_fma_f32 v37, -v37, v50, v39
	v_div_fmas_f32 v37, v37, v38, v50
	v_div_fixup_f32 v34, v37, v36, v34
	v_pk_add_f32 v[36:37], v[76:77], v[40:41]
	s_nop 0
	v_mul_f32_e32 v38, 0xbfb8aa3b, v36
	v_mul_f32_e32 v39, 0xbfb8aa3b, v37
	v_exp_f32_e32 v38, v38
	v_exp_f32_e32 v39, v39
	s_nop 0
	v_pk_add_f32 v[38:39], v[38:39], 1.0 op_sel_hi:[1,0]
	s_nop 0
	v_div_scale_f32 v40, s[14:15], v39, v39, v37
	v_rcp_f32_e32 v41, v40
	s_nop 0
	v_fma_f32 v50, -v40, v41, 1.0
	v_fmac_f32_e32 v41, v50, v41
	v_div_scale_f32 v50, vcc, v37, v39, v37
	v_mul_f32_e32 v51, v50, v41
	v_fma_f32 v52, -v40, v51, v50
	v_fmac_f32_e32 v51, v52, v41
	v_fma_f32 v40, -v40, v51, v50
	v_div_fmas_f32 v40, v40, v41, v51
	v_div_fixup_f32 v37, v40, v39, v37
	v_div_scale_f32 v39, s[14:15], v38, v38, v36
	v_rcp_f32_e32 v40, v39
	s_nop 0
	v_fma_f32 v41, -v39, v40, 1.0
	v_fmac_f32_e32 v40, v41, v40
	v_div_scale_f32 v41, vcc, v36, v38, v36
	v_mul_f32_e32 v50, v41, v40
	v_fma_f32 v51, -v39, v50, v41
	v_fmac_f32_e32 v50, v51, v40
	v_fma_f32 v39, -v39, v50, v41
	v_div_fmas_f32 v39, v39, v40, v50
	v_div_fixup_f32 v36, v39, v38, v36
	ds_write_b128 v0, v[34:37] offset:160
	v_pk_add_f32 v[34:35], v[70:71], v[42:43]
	s_nop 0
	v_mul_f32_e32 v36, 0xbfb8aa3b, v34
	v_mul_f32_e32 v37, 0xbfb8aa3b, v35
	v_exp_f32_e32 v36, v36
	v_exp_f32_e32 v37, v37
	s_nop 0
	v_pk_add_f32 v[36:37], v[36:37], 1.0 op_sel_hi:[1,0]
	s_nop 0
	v_div_scale_f32 v38, s[14:15], v37, v37, v35
	v_rcp_f32_e32 v39, v38
	s_nop 0
	v_fma_f32 v40, -v38, v39, 1.0
	v_fmac_f32_e32 v39, v40, v39
	v_div_scale_f32 v40, vcc, v35, v37, v35
	v_mul_f32_e32 v41, v40, v39
	v_fma_f32 v42, -v38, v41, v40
	v_fmac_f32_e32 v41, v42, v39
	v_fma_f32 v38, -v38, v41, v40
	v_div_fmas_f32 v38, v38, v39, v41
	v_div_fixup_f32 v35, v38, v37, v35
	v_div_scale_f32 v37, s[14:15], v36, v36, v34
	v_rcp_f32_e32 v38, v37
	s_nop 0
	v_fma_f32 v39, -v37, v38, 1.0
	v_fmac_f32_e32 v38, v39, v38
	v_div_scale_f32 v39, vcc, v34, v36, v34
	v_mul_f32_e32 v40, v39, v38
	v_fma_f32 v41, -v37, v40, v39
	v_fmac_f32_e32 v40, v41, v38
	v_fma_f32 v37, -v37, v40, v39
	v_div_fmas_f32 v37, v37, v38, v40
	v_div_fixup_f32 v34, v37, v36, v34
	v_pk_add_f32 v[36:37], v[72:73], v[44:45]
	s_nop 0
	v_mul_f32_e32 v38, 0xbfb8aa3b, v36
	v_mul_f32_e32 v39, 0xbfb8aa3b, v37
	v_exp_f32_e32 v38, v38
	v_exp_f32_e32 v39, v39
	s_nop 0
	v_pk_add_f32 v[38:39], v[38:39], 1.0 op_sel_hi:[1,0]
	s_nop 0
	v_div_scale_f32 v40, s[14:15], v39, v39, v37
	v_rcp_f32_e32 v41, v40
	s_nop 0
	v_fma_f32 v42, -v40, v41, 1.0
	v_fmac_f32_e32 v41, v42, v41
	v_div_scale_f32 v42, vcc, v37, v39, v37
	v_mul_f32_e32 v43, v42, v41
	v_fma_f32 v44, -v40, v43, v42
	v_fmac_f32_e32 v43, v44, v41
	v_fma_f32 v40, -v40, v43, v42
	v_div_fmas_f32 v40, v40, v41, v43
	v_div_fixup_f32 v37, v40, v39, v37
	v_div_scale_f32 v39, s[14:15], v38, v38, v36
	v_rcp_f32_e32 v40, v39
	s_nop 0
	v_fma_f32 v41, -v39, v40, 1.0
	v_fmac_f32_e32 v40, v41, v40
	v_div_scale_f32 v41, vcc, v36, v38, v36
	v_mul_f32_e32 v42, v41, v40
	v_fma_f32 v43, -v39, v42, v41
	v_fmac_f32_e32 v42, v43, v40
	v_fma_f32 v39, -v39, v42, v41
	v_div_fmas_f32 v39, v39, v40, v42
	v_div_fixup_f32 v36, v39, v38, v36
	ds_write_b128 v0, v[34:37] offset:192
	v_pk_add_f32 v[34:35], v[66:67], v[46:47]
	s_nop 0
	v_mul_f32_e32 v36, 0xbfb8aa3b, v34
	v_mul_f32_e32 v37, 0xbfb8aa3b, v35
	v_exp_f32_e32 v36, v36
	v_exp_f32_e32 v37, v37
	s_nop 0
	v_pk_add_f32 v[36:37], v[36:37], 1.0 op_sel_hi:[1,0]
	s_nop 0
	v_div_scale_f32 v38, s[14:15], v37, v37, v35
	v_rcp_f32_e32 v39, v38
	s_nop 0
	v_fma_f32 v40, -v38, v39, 1.0
	v_fmac_f32_e32 v39, v40, v39
	v_div_scale_f32 v40, vcc, v35, v37, v35
	v_mul_f32_e32 v41, v40, v39
	v_fma_f32 v42, -v38, v41, v40
	v_fmac_f32_e32 v41, v42, v39
	v_fma_f32 v38, -v38, v41, v40
	v_div_fmas_f32 v38, v38, v39, v41
	v_div_fixup_f32 v35, v38, v37, v35
	v_div_scale_f32 v37, s[14:15], v36, v36, v34
	v_rcp_f32_e32 v38, v37
	s_nop 0
	v_fma_f32 v39, -v37, v38, 1.0
	v_fmac_f32_e32 v38, v39, v38
	v_div_scale_f32 v39, vcc, v34, v36, v34
	v_mul_f32_e32 v40, v39, v38
	v_fma_f32 v41, -v37, v40, v39
	v_fmac_f32_e32 v40, v41, v38
	v_fma_f32 v37, -v37, v40, v39
	v_div_fmas_f32 v37, v37, v38, v40
	v_div_fixup_f32 v34, v37, v36, v34
	v_pk_add_f32 v[36:37], v[68:69], v[48:49]
	s_nop 0
	v_mul_f32_e32 v38, 0xbfb8aa3b, v36
	v_mul_f32_e32 v39, 0xbfb8aa3b, v37
	v_exp_f32_e32 v38, v38
	v_exp_f32_e32 v39, v39
	s_nop 0
	v_pk_add_f32 v[38:39], v[38:39], 1.0 op_sel_hi:[1,0]
	s_nop 0
	v_div_scale_f32 v40, s[14:15], v39, v39, v37
	v_rcp_f32_e32 v41, v40
	s_nop 0
	v_fma_f32 v42, -v40, v41, 1.0
	v_fmac_f32_e32 v41, v42, v41
	v_div_scale_f32 v42, vcc, v37, v39, v37
	v_mul_f32_e32 v43, v42, v41
	v_fma_f32 v44, -v40, v43, v42
	v_fmac_f32_e32 v43, v44, v41
	v_fma_f32 v40, -v40, v43, v42
	v_div_fmas_f32 v40, v40, v41, v43
	v_div_fixup_f32 v37, v40, v39, v37
	v_div_scale_f32 v39, s[14:15], v38, v38, v36
	v_rcp_f32_e32 v40, v39
	s_nop 0
	v_fma_f32 v41, -v39, v40, 1.0
	v_fmac_f32_e32 v40, v41, v40
	v_div_scale_f32 v41, vcc, v36, v38, v36
	v_mul_f32_e32 v42, v41, v40
	v_fma_f32 v43, -v39, v42, v41
	v_fmac_f32_e32 v42, v43, v40
	v_fma_f32 v39, -v39, v42, v41
	v_div_fmas_f32 v39, v39, v40, v42
; DI float siluf_(float x) { return x / (1.f + __expf(-x)); }
; DI void compress_item(const Params& p, int l, int item, char* lds) {
;     ...
;   float* hid = (float*)lds;
; #pragma unroll
;   for (int mi = 0; mi < 2; ++mi)
; #pragma unroll
;     for (int ni = 0; ni < 2; ++ni)
; #pragma unroll
;       for (int i = 0; i < 16; ++i) {
;         const int row = wm * 64 + mi * 32 + r, col = wn * 64 + ni * 32 + (i & 3) + 8 * (i >> 2) + 4 * h;
;         hid[row * 132 + col] = siluf_(acc[mi][ni][i] + pw[ni][i]);
;       }
	v_div_fixup_f32 v36, v39, v38, v36
	ds_write_b128 v0, v[34:37] offset:224
	v_mul_f32_e32 v34, 0xbfb8aa3b, v18
	v_mul_f32_e32 v35, 0xbfb8aa3b, v19
	v_exp_f32_e32 v34, v34
	v_exp_f32_e32 v35, v35
	v_and_b32_e32 v43, 63, v162
	v_pk_add_f32 v[34:35], v[34:35], 1.0 op_sel_hi:[1,0]
	s_nop 0
	v_div_scale_f32 v36, s[14:15], v35, v35, v19
	v_rcp_f32_e32 v37, v36
	s_nop 0
	v_fma_f32 v38, -v36, v37, 1.0
	v_fmac_f32_e32 v37, v38, v37
	v_div_scale_f32 v38, vcc, v19, v35, v19
	v_mul_f32_e32 v39, v38, v37
	v_fma_f32 v40, -v36, v39, v38
	v_fmac_f32_e32 v39, v40, v37
	v_fma_f32 v36, -v36, v39, v38
	v_div_fmas_f32 v36, v36, v37, v39
	v_div_fixup_f32 v19, v36, v35, v19
	v_div_scale_f32 v35, s[14:15], v34, v34, v18
	v_rcp_f32_e32 v36, v35
	s_nop 0
	v_fma_f32 v37, -v35, v36, 1.0
	v_fmac_f32_e32 v36, v37, v36
	v_div_scale_f32 v37, vcc, v18, v34, v18
	v_mul_f32_e32 v38, v37, v36
	v_fma_f32 v39, -v35, v38, v37
	v_fmac_f32_e32 v38, v39, v36
	v_fma_f32 v35, -v35, v38, v37
	v_div_fmas_f32 v35, v35, v36, v38
	v_div_fixup_f32 v18, v35, v34, v18
	v_mul_f32_e32 v34, 0xbfb8aa3b, v20
	v_mul_f32_e32 v35, 0xbfb8aa3b, v21
	v_exp_f32_e32 v34, v34
	v_exp_f32_e32 v35, v35
	s_nop 0
	v_pk_add_f32 v[34:35], v[34:35], 1.0 op_sel_hi:[1,0]
	s_nop 0
	v_div_scale_f32 v36, s[14:15], v35, v35, v21
	v_rcp_f32_e32 v37, v36
	s_nop 0
	v_fma_f32 v38, -v36, v37, 1.0
	v_fmac_f32_e32 v37, v38, v37
	v_div_scale_f32 v38, vcc, v21, v35, v21
	v_mul_f32_e32 v39, v38, v37
	v_fma_f32 v40, -v36, v39, v38
	v_fmac_f32_e32 v39, v40, v37
	v_fma_f32 v36, -v36, v39, v38
	v_div_fmas_f32 v36, v36, v37, v39
	v_div_fixup_f32 v21, v36, v35, v21
	v_div_scale_f32 v35, s[14:15], v34, v34, v20
	v_rcp_f32_e32 v36, v35
	s_nop 0
	v_fma_f32 v37, -v35, v36, 1.0
	v_fmac_f32_e32 v36, v37, v36
	v_div_scale_f32 v37, vcc, v20, v34, v20
	v_mul_f32_e32 v38, v37, v36
	v_fma_f32 v39, -v35, v38, v37
	v_fmac_f32_e32 v38, v39, v36
	v_fma_f32 v35, -v35, v38, v37
	v_div_fmas_f32 v35, v35, v36, v38
	v_div_fixup_f32 v20, v35, v34, v20
	ds_write_b128 v0, v[18:21] offset:16896
	v_pk_add_f32 v[18:19], v[90:91], v[22:23]
	s_nop 0
	v_mul_f32_e32 v20, 0xbfb8aa3b, v18
	v_mul_f32_e32 v21, 0xbfb8aa3b, v19
	v_exp_f32_e32 v20, v20
	v_exp_f32_e32 v21, v21
	s_nop 0
	v_pk_add_f32 v[20:21], v[20:21], 1.0 op_sel_hi:[1,0]
	s_nop 0
	v_div_scale_f32 v22, s[14:15], v21, v21, v19
	v_rcp_f32_e32 v23, v22
	s_nop 0
	v_fma_f32 v34, -v22, v23, 1.0
	v_fmac_f32_e32 v23, v34, v23
	v_div_scale_f32 v34, vcc, v19, v21, v19
	v_mul_f32_e32 v35, v34, v23
	v_fma_f32 v36, -v22, v35, v34
	v_fmac_f32_e32 v35, v36, v23
	v_fma_f32 v22, -v22, v35, v34
	v_div_fmas_f32 v22, v22, v23, v35
	v_div_fixup_f32 v19, v22, v21, v19
	v_div_scale_f32 v21, s[14:15], v20, v20, v18
	v_rcp_f32_e32 v22, v21
	s_nop 0
	v_fma_f32 v23, -v21, v22, 1.0
	v_fmac_f32_e32 v22, v23, v22
	v_div_scale_f32 v23, vcc, v18, v20, v18
	v_mul_f32_e32 v34, v23, v22
	v_fma_f32 v35, -v21, v34, v23
	v_fmac_f32_e32 v34, v35, v22
	v_fma_f32 v21, -v21, v34, v23
	v_div_fmas_f32 v21, v21, v22, v34
	v_div_fixup_f32 v18, v21, v20, v18
	v_pk_add_f32 v[20:21], v[92:93], v[24:25]
	s_nop 0
	v_mul_f32_e32 v22, 0xbfb8aa3b, v20
	v_mul_f32_e32 v23, 0xbfb8aa3b, v21
	v_exp_f32_e32 v22, v22
	v_exp_f32_e32 v23, v23
	s_nop 0
	v_pk_add_f32 v[22:23], v[22:23], 1.0 op_sel_hi:[1,0]
	s_nop 0
	v_div_scale_f32 v24, s[14:15], v23, v23, v21
	v_rcp_f32_e32 v25, v24
	s_nop 0
	v_fma_f32 v34, -v24, v25, 1.0
	v_fmac_f32_e32 v25, v34, v25
	v_div_scale_f32 v34, vcc, v21, v23, v21
	v_mul_f32_e32 v35, v34, v25
	v_fma_f32 v36, -v24, v35, v34
	v_fmac_f32_e32 v35, v36, v25
	v_fma_f32 v24, -v24, v35, v34
	v_div_fmas_f32 v24, v24, v25, v35
	v_div_fixup_f32 v21, v24, v23, v21
	v_div_scale_f32 v23, s[14:15], v22, v22, v20
	v_rcp_f32_e32 v24, v23
	s_nop 0
	v_fma_f32 v25, -v23, v24, 1.0
	v_fmac_f32_e32 v24, v25, v24
	v_div_scale_f32 v25, vcc, v20, v22, v20
	v_mul_f32_e32 v34, v25, v24
	v_fma_f32 v35, -v23, v34, v25
	v_fmac_f32_e32 v34, v35, v24
	v_fma_f32 v23, -v23, v34, v25
	v_div_fmas_f32 v23, v23, v24, v34
	v_div_fixup_f32 v20, v23, v22, v20
	ds_write_b128 v0, v[18:21] offset:16928
	v_pk_add_f32 v[18:19], v[86:87], v[26:27]
	s_nop 0
	v_mul_f32_e32 v20, 0xbfb8aa3b, v18
	v_mul_f32_e32 v21, 0xbfb8aa3b, v19
	v_exp_f32_e32 v20, v20
	v_exp_f32_e32 v21, v21
	s_nop 0
	v_pk_add_f32 v[20:21], v[20:21], 1.0 op_sel_hi:[1,0]
	s_nop 0
	v_div_scale_f32 v22, s[14:15], v21, v21, v19
	v_rcp_f32_e32 v23, v22
	s_nop 0
	v_fma_f32 v24, -v22, v23, 1.0
	v_fmac_f32_e32 v23, v24, v23
	v_div_scale_f32 v24, vcc, v19, v21, v19
	v_mul_f32_e32 v25, v24, v23
	v_fma_f32 v26, -v22, v25, v24
	v_fmac_f32_e32 v25, v26, v23
	v_fma_f32 v22, -v22, v25, v24
	v_div_fmas_f32 v22, v22, v23, v25
	v_div_fixup_f32 v19, v22, v21, v19
	v_div_scale_f32 v21, s[14:15], v20, v20, v18
	v_rcp_f32_e32 v22, v21
	s_nop 0
	v_fma_f32 v23, -v21, v22, 1.0
	v_fmac_f32_e32 v22, v23, v22
	v_div_scale_f32 v23, vcc, v18, v20, v18
	v_mul_f32_e32 v24, v23, v22
	v_fma_f32 v25, -v21, v24, v23
	v_fmac_f32_e32 v24, v25, v22
	v_fma_f32 v21, -v21, v24, v23
	v_div_fmas_f32 v21, v21, v22, v24
	v_div_fixup_f32 v18, v21, v20, v18
	v_pk_add_f32 v[20:21], v[88:89], v[28:29]
	v_mov_b32_e32 v29, v1
	v_mul_f32_e32 v22, 0xbfb8aa3b, v20
	v_mul_f32_e32 v23, 0xbfb8aa3b, v21
	v_exp_f32_e32 v22, v22
	v_exp_f32_e32 v23, v23
	s_nop 0
	v_pk_add_f32 v[22:23], v[22:23], 1.0 op_sel_hi:[1,0]
	s_nop 0
	v_div_scale_f32 v24, s[14:15], v23, v23, v21
	v_rcp_f32_e32 v25, v24
	s_nop 0
	v_fma_f32 v26, -v24, v25, 1.0
	v_fmac_f32_e32 v25, v26, v25
	v_div_scale_f32 v26, vcc, v21, v23, v21
	v_mul_f32_e32 v27, v26, v25
	v_fma_f32 v28, -v24, v27, v26
	v_fmac_f32_e32 v27, v28, v25
	v_fma_f32 v24, -v24, v27, v26
	v_div_fmas_f32 v24, v24, v25, v27
	v_div_fixup_f32 v21, v24, v23, v21
; DI float siluf_(float x) { return x / (1.f + __expf(-x)); }
; DI void compress_item(const Params& p, int l, int item, char* lds) {
;     ...
;   float* hid = (float*)lds;
; #pragma unroll
;   for (int mi = 0; mi < 2; ++mi)
; #pragma unroll
;     for (int ni = 0; ni < 2; ++ni)
; #pragma unroll
;       for (int i = 0; i < 16; ++i) {
;         const int row = wm * 64 + mi * 32 + r, col = wn * 64 + ni * 32 + (i & 3) + 8 * (i >> 2) + 4 * h;
;         hid[row * 132 + col] = siluf_(acc[mi][ni][i] + pw[ni][i]);
;       }
	v_div_scale_f32 v23, s[14:15], v22, v22, v20
	v_rcp_f32_e32 v24, v23
	s_nop 0
	v_fma_f32 v25, -v23, v24, 1.0
	v_fmac_f32_e32 v24, v25, v24
	v_div_scale_f32 v25, vcc, v20, v22, v20
	v_mul_f32_e32 v26, v25, v24
	v_fma_f32 v27, -v23, v26, v25
	v_fmac_f32_e32 v26, v27, v24
	v_fma_f32 v23, -v23, v26, v25
	v_div_fmas_f32 v23, v23, v24, v26
	v_div_fixup_f32 v20, v23, v22, v20
	ds_write_b128 v0, v[18:21] offset:16960
	v_pk_add_f32 v[18:19], v[82:83], v[30:31]
	s_nop 0
	v_mul_f32_e32 v20, 0xbfb8aa3b, v18
	v_mul_f32_e32 v21, 0xbfb8aa3b, v19
	v_exp_f32_e32 v20, v20
	v_exp_f32_e32 v21, v21
	s_nop 0
	v_pk_add_f32 v[20:21], v[20:21], 1.0 op_sel_hi:[1,0]
	s_nop 0
	v_div_scale_f32 v22, s[14:15], v21, v21, v19
	v_rcp_f32_e32 v23, v22
	s_nop 0
	v_fma_f32 v24, -v22, v23, 1.0
	v_fmac_f32_e32 v23, v24, v23
	v_div_scale_f32 v24, vcc, v19, v21, v19
	v_mul_f32_e32 v25, v24, v23
	v_fma_f32 v26, -v22, v25, v24
	v_fmac_f32_e32 v25, v26, v23
	v_fma_f32 v22, -v22, v25, v24
	v_div_fmas_f32 v22, v22, v23, v25
	v_div_fixup_f32 v19, v22, v21, v19
	v_div_scale_f32 v21, s[14:15], v20, v20, v18
	v_rcp_f32_e32 v22, v21
	s_nop 0
	v_fma_f32 v23, -v21, v22, 1.0
	v_fmac_f32_e32 v22, v23, v22
	v_div_scale_f32 v23, vcc, v18, v20, v18
	v_mul_f32_e32 v24, v23, v22
	v_fma_f32 v25, -v21, v24, v23
	v_fmac_f32_e32 v24, v25, v22
	v_fma_f32 v21, -v21, v24, v23
	v_div_fmas_f32 v21, v21, v22, v24
	v_div_fixup_f32 v18, v21, v20, v18
	v_pk_add_f32 v[20:21], v[84:85], v[32:33]
	s_nop 0
	v_mul_f32_e32 v22, 0xbfb8aa3b, v20
	v_mul_f32_e32 v23, 0xbfb8aa3b, v21
	v_exp_f32_e32 v22, v22
	v_exp_f32_e32 v23, v23
	s_nop 0
	v_pk_add_f32 v[22:23], v[22:23], 1.0 op_sel_hi:[1,0]
	s_nop 0
	v_div_scale_f32 v24, s[14:15], v23, v23, v21
	v_rcp_f32_e32 v25, v24
	s_nop 0
	v_fma_f32 v26, -v24, v25, 1.0
	v_fmac_f32_e32 v25, v26, v25
	v_div_scale_f32 v26, vcc, v21, v23, v21
	v_mul_f32_e32 v27, v26, v25
	v_fma_f32 v28, -v24, v27, v26
	v_fmac_f32_e32 v27, v28, v25
	v_fma_f32 v24, -v24, v27, v26
	v_div_fmas_f32 v24, v24, v25, v27
	v_div_fixup_f32 v21, v24, v23, v21
	v_div_scale_f32 v23, s[14:15], v22, v22, v20
	v_rcp_f32_e32 v24, v23
	v_lshlrev_b32_e32 v28, 2, v43
	v_fma_f32 v25, -v23, v24, 1.0
	v_fmac_f32_e32 v24, v25, v24
	v_div_scale_f32 v25, vcc, v20, v22, v20
	v_mul_f32_e32 v26, v25, v24
	v_fma_f32 v27, -v23, v26, v25
	v_fmac_f32_e32 v26, v27, v24
	v_fma_f32 v23, -v23, v26, v25
	v_div_fmas_f32 v23, v23, v24, v26
	v_div_fixup_f32 v20, v23, v22, v20
	ds_write_b128 v0, v[18:21] offset:16992
	v_mul_f32_e32 v18, 0xbfb8aa3b, v2
	v_mul_f32_e32 v19, 0xbfb8aa3b, v3
	v_exp_f32_e32 v18, v18
	v_exp_f32_e32 v19, v19
	s_nop 0
	v_pk_add_f32 v[18:19], v[18:19], 1.0 op_sel_hi:[1,0]
	s_nop 0
	v_div_scale_f32 v20, s[14:15], v19, v19, v3
	v_rcp_f32_e32 v21, v20
	s_nop 0
	v_fma_f32 v22, -v20, v21, 1.0
	v_fmac_f32_e32 v21, v22, v21
	v_div_scale_f32 v22, vcc, v3, v19, v3
	v_mul_f32_e32 v23, v22, v21
	v_fma_f32 v24, -v20, v23, v22
	v_fmac_f32_e32 v23, v24, v21
	v_fma_f32 v20, -v20, v23, v22
	v_div_fmas_f32 v20, v20, v21, v23
	v_div_fixup_f32 v3, v20, v19, v3
	v_div_scale_f32 v19, s[14:15], v18, v18, v2
	v_rcp_f32_e32 v20, v19
	s_nop 0
	v_fma_f32 v21, -v19, v20, 1.0
	v_fmac_f32_e32 v20, v21, v20
	v_div_scale_f32 v21, vcc, v2, v18, v2
	v_mul_f32_e32 v22, v21, v20
	v_fma_f32 v23, -v19, v22, v21
	v_fmac_f32_e32 v22, v23, v20
	v_fma_f32 v19, -v19, v22, v21
	v_div_fmas_f32 v19, v19, v20, v22
	v_div_fixup_f32 v2, v19, v18, v2
	v_mul_f32_e32 v18, 0xbfb8aa3b, v4
	v_mul_f32_e32 v19, 0xbfb8aa3b, v5
	v_exp_f32_e32 v18, v18
	v_exp_f32_e32 v19, v19
	s_nop 0
	v_pk_add_f32 v[18:19], v[18:19], 1.0 op_sel_hi:[1,0]
	s_nop 0
	v_div_scale_f32 v20, s[14:15], v19, v19, v5
	v_rcp_f32_e32 v21, v20
	s_nop 0
	v_fma_f32 v22, -v20, v21, 1.0
	v_fmac_f32_e32 v21, v22, v21
	v_div_scale_f32 v22, vcc, v5, v19, v5
	v_mul_f32_e32 v23, v22, v21
	v_fma_f32 v24, -v20, v23, v22
	v_fmac_f32_e32 v23, v24, v21
	v_fma_f32 v20, -v20, v23, v22
	v_div_fmas_f32 v20, v20, v21, v23
	v_div_fixup_f32 v5, v20, v19, v5
	v_div_scale_f32 v19, s[14:15], v18, v18, v4
	v_rcp_f32_e32 v20, v19
	s_nop 0
	v_fma_f32 v21, -v19, v20, 1.0
	v_fmac_f32_e32 v20, v21, v20
	v_div_scale_f32 v21, vcc, v4, v18, v4
	v_mul_f32_e32 v22, v21, v20
	v_fma_f32 v23, -v19, v22, v21
	v_fmac_f32_e32 v22, v23, v20
	v_fma_f32 v19, -v19, v22, v21
	v_div_fmas_f32 v19, v19, v20, v22
	v_div_fixup_f32 v4, v19, v18, v4
	ds_write_b128 v0, v[2:5] offset:17024
	v_pk_add_f32 v[2:3], v[74:75], v[6:7]
	s_nop 0
	v_mul_f32_e32 v4, 0xbfb8aa3b, v2
	v_mul_f32_e32 v5, 0xbfb8aa3b, v3
	v_exp_f32_e32 v4, v4
	v_exp_f32_e32 v5, v5
	s_nop 0
	v_pk_add_f32 v[4:5], v[4:5], 1.0 op_sel_hi:[1,0]
	s_nop 0
	v_div_scale_f32 v6, s[14:15], v5, v5, v3
	v_rcp_f32_e32 v7, v6
	s_nop 0
	v_fma_f32 v18, -v6, v7, 1.0
	v_fmac_f32_e32 v7, v18, v7
	v_div_scale_f32 v18, vcc, v3, v5, v3
	v_mul_f32_e32 v19, v18, v7
	v_fma_f32 v20, -v6, v19, v18
	v_fmac_f32_e32 v19, v20, v7
	v_fma_f32 v6, -v6, v19, v18
	v_div_fmas_f32 v6, v6, v7, v19
	v_div_fixup_f32 v3, v6, v5, v3
	v_div_scale_f32 v5, s[14:15], v4, v4, v2
	v_rcp_f32_e32 v6, v5
	s_nop 0
	v_fma_f32 v7, -v5, v6, 1.0
	v_fmac_f32_e32 v6, v7, v6
	v_div_scale_f32 v7, vcc, v2, v4, v2
	v_mul_f32_e32 v18, v7, v6
	v_fma_f32 v19, -v5, v18, v7
	v_fmac_f32_e32 v18, v19, v6
	v_fma_f32 v5, -v5, v18, v7
	v_div_fmas_f32 v5, v5, v6, v18
	v_div_fixup_f32 v2, v5, v4, v2
	v_pk_add_f32 v[4:5], v[76:77], v[8:9]
	s_nop 0
	v_mul_f32_e32 v6, 0xbfb8aa3b, v4
	v_mul_f32_e32 v7, 0xbfb8aa3b, v5
	v_exp_f32_e32 v6, v6
	v_exp_f32_e32 v7, v7
	s_nop 0
	v_pk_add_f32 v[6:7], v[6:7], 1.0 op_sel_hi:[1,0]
	s_nop 0
	v_div_scale_f32 v8, s[14:15], v7, v7, v5
	v_rcp_f32_e32 v9, v8
	s_nop 0
	v_fma_f32 v18, -v8, v9, 1.0
	v_fmac_f32_e32 v9, v18, v9
; DI float siluf_(float x) { return x / (1.f + __expf(-x)); }
; DI void compress_item(const Params& p, int l, int item, char* lds) {
;     ...
;   float* hid = (float*)lds;
; #pragma unroll
;   for (int mi = 0; mi < 2; ++mi)
; #pragma unroll
;     for (int ni = 0; ni < 2; ++ni)
; #pragma unroll
;       for (int i = 0; i < 16; ++i) {
;         const int row = wm * 64 + mi * 32 + r, col = wn * 64 + ni * 32 + (i & 3) + 8 * (i >> 2) + 4 * h;
;         hid[row * 132 + col] = siluf_(acc[mi][ni][i] + pw[ni][i]);
;       }
;   __syncthreads();
;   {
;     const int e = tid & 63, rq = tid >> 6;
;     float o[32];
; #pragma unroll
;     for (int i = 0; i < 32; ++i) o[i] = 0.f;
;     for (int n = 0; n < 128; n += 4) {
	v_div_scale_f32 v18, vcc, v5, v7, v5
	v_mul_f32_e32 v19, v18, v9
	v_fma_f32 v20, -v8, v19, v18
	v_fmac_f32_e32 v19, v20, v9
	v_fma_f32 v8, -v8, v19, v18
	v_div_fmas_f32 v8, v8, v9, v19
	v_div_fixup_f32 v5, v8, v7, v5
	v_div_scale_f32 v7, s[14:15], v6, v6, v4
	v_rcp_f32_e32 v8, v7
	s_nop 0
	v_fma_f32 v9, -v7, v8, 1.0
	v_fmac_f32_e32 v8, v9, v8
	v_div_scale_f32 v9, vcc, v4, v6, v4
	v_mul_f32_e32 v18, v9, v8
	v_fma_f32 v19, -v7, v18, v9
	v_fmac_f32_e32 v18, v19, v8
	v_fma_f32 v7, -v7, v18, v9
	v_div_fmas_f32 v7, v7, v8, v18
	v_div_fixup_f32 v4, v7, v6, v4
	ds_write_b128 v0, v[2:5] offset:17056
	v_pk_add_f32 v[2:3], v[70:71], v[10:11]
	s_nop 0
	v_mul_f32_e32 v4, 0xbfb8aa3b, v2
	v_mul_f32_e32 v5, 0xbfb8aa3b, v3
	v_exp_f32_e32 v4, v4
	v_exp_f32_e32 v5, v5
	s_nop 0
	v_pk_add_f32 v[4:5], v[4:5], 1.0 op_sel_hi:[1,0]
	s_nop 0
	v_div_scale_f32 v6, s[14:15], v5, v5, v3
	v_rcp_f32_e32 v7, v6
	s_nop 0
	v_fma_f32 v8, -v6, v7, 1.0
	v_fmac_f32_e32 v7, v8, v7
	v_div_scale_f32 v8, vcc, v3, v5, v3
	v_mul_f32_e32 v9, v8, v7
	v_fma_f32 v10, -v6, v9, v8
	v_fmac_f32_e32 v9, v10, v7
	v_fma_f32 v6, -v6, v9, v8
	v_div_fmas_f32 v6, v6, v7, v9
	v_div_fixup_f32 v3, v6, v5, v3
	v_div_scale_f32 v5, s[14:15], v4, v4, v2
	v_rcp_f32_e32 v6, v5
	s_nop 0
	v_fma_f32 v7, -v5, v6, 1.0
	v_fmac_f32_e32 v6, v7, v6
	v_div_scale_f32 v7, vcc, v2, v4, v2
	v_mul_f32_e32 v8, v7, v6
	v_fma_f32 v9, -v5, v8, v7
	v_fmac_f32_e32 v8, v9, v6
	v_fma_f32 v5, -v5, v8, v7
	v_div_fmas_f32 v5, v5, v6, v8
	v_div_fixup_f32 v2, v5, v4, v2
	v_pk_add_f32 v[4:5], v[72:73], v[12:13]
	s_nop 0
	v_mul_f32_e32 v6, 0xbfb8aa3b, v4
	v_mul_f32_e32 v7, 0xbfb8aa3b, v5
	v_exp_f32_e32 v6, v6
	v_exp_f32_e32 v7, v7
	s_nop 0
	v_pk_add_f32 v[6:7], v[6:7], 1.0 op_sel_hi:[1,0]
	s_nop 0
	v_div_scale_f32 v8, s[14:15], v7, v7, v5
	v_rcp_f32_e32 v9, v8
	s_nop 0
	v_fma_f32 v10, -v8, v9, 1.0
	v_fmac_f32_e32 v9, v10, v9
	v_div_scale_f32 v10, vcc, v5, v7, v5
	v_mul_f32_e32 v11, v10, v9
	v_fma_f32 v12, -v8, v11, v10
	v_fmac_f32_e32 v11, v12, v9
	v_fma_f32 v8, -v8, v11, v10
	v_div_fmas_f32 v8, v8, v9, v11
	v_div_fixup_f32 v5, v8, v7, v5
	v_div_scale_f32 v7, s[14:15], v6, v6, v4
	v_rcp_f32_e32 v8, v7
	s_nop 0
	v_fma_f32 v9, -v7, v8, 1.0
	v_fmac_f32_e32 v8, v9, v8
	v_div_scale_f32 v9, vcc, v4, v6, v4
	v_mul_f32_e32 v10, v9, v8
	v_fma_f32 v11, -v7, v10, v9
	v_fmac_f32_e32 v10, v11, v8
	v_fma_f32 v7, -v7, v10, v9
	v_div_fmas_f32 v7, v7, v8, v10
	v_div_fixup_f32 v4, v7, v6, v4
	ds_write_b128 v0, v[2:5] offset:17088
	v_pk_add_f32 v[2:3], v[66:67], v[14:15]
	s_nop 0
	v_mul_f32_e32 v4, 0xbfb8aa3b, v2
	v_mul_f32_e32 v5, 0xbfb8aa3b, v3
	v_exp_f32_e32 v4, v4
	v_exp_f32_e32 v5, v5
	s_nop 0
	v_pk_add_f32 v[4:5], v[4:5], 1.0 op_sel_hi:[1,0]
	s_nop 0
	v_div_scale_f32 v6, s[14:15], v5, v5, v3
	v_rcp_f32_e32 v7, v6
	s_nop 0
	v_fma_f32 v8, -v6, v7, 1.0
	v_fmac_f32_e32 v7, v8, v7
	v_div_scale_f32 v8, vcc, v3, v5, v3
	v_mul_f32_e32 v9, v8, v7
	v_fma_f32 v10, -v6, v9, v8
	v_fmac_f32_e32 v9, v10, v7
	v_fma_f32 v6, -v6, v9, v8
	v_div_fmas_f32 v6, v6, v7, v9
	v_div_fixup_f32 v3, v6, v5, v3
	v_div_scale_f32 v5, s[14:15], v4, v4, v2
	v_rcp_f32_e32 v6, v5
	s_nop 0
	v_fma_f32 v7, -v5, v6, 1.0
	v_fmac_f32_e32 v6, v7, v6
	v_div_scale_f32 v7, vcc, v2, v4, v2
	v_mul_f32_e32 v8, v7, v6
	v_fma_f32 v9, -v5, v8, v7
	v_fmac_f32_e32 v8, v9, v6
	v_fma_f32 v5, -v5, v8, v7
	v_div_fmas_f32 v5, v5, v6, v8
	v_div_fixup_f32 v2, v5, v4, v2
	v_pk_add_f32 v[4:5], v[68:69], v[16:17]
	s_nop 0
	v_mul_f32_e32 v6, 0xbfb8aa3b, v4
	v_mul_f32_e32 v7, 0xbfb8aa3b, v5
	v_exp_f32_e32 v6, v6
	v_exp_f32_e32 v7, v7
	s_nop 0
	v_pk_add_f32 v[6:7], v[6:7], 1.0 op_sel_hi:[1,0]
	s_nop 0
	v_div_scale_f32 v8, s[14:15], v7, v7, v5
	v_rcp_f32_e32 v9, v8
	s_nop 0
	v_fma_f32 v10, -v8, v9, 1.0
	v_fmac_f32_e32 v9, v10, v9
	v_div_scale_f32 v10, vcc, v5, v7, v5
	v_mul_f32_e32 v11, v10, v9
	v_fma_f32 v12, -v8, v11, v10
	v_fmac_f32_e32 v11, v12, v9
	v_fma_f32 v8, -v8, v11, v10
	v_div_fmas_f32 v8, v8, v9, v11
	v_div_fixup_f32 v5, v8, v7, v5
	v_div_scale_f32 v7, s[14:15], v6, v6, v4
	v_rcp_f32_e32 v8, v7
	s_movk_i32 s14, 0x4200
	v_mul_lo_u32 v39, v163, s14
	s_add_u32 s14, s13, s6
	v_fma_f32 v9, -v7, v8, 1.0
	v_fmac_f32_e32 v8, v9, v8
	v_div_scale_f32 v9, vcc, v4, v6, v4
	v_mul_f32_e32 v10, v9, v8
	v_fma_f32 v11, -v7, v10, v9
	v_fmac_f32_e32 v10, v11, v8
	v_fma_f32 v7, -v7, v10, v9
	v_div_fmas_f32 v7, v7, v8, v10
	v_div_fixup_f32 v4, v7, v6, v4
	s_addc_u32 s15, s12, s7
	ds_write_b128 v0, v[2:5] offset:17120
	v_lshl_add_u64 v[2:3], s[14:15], 0, v[28:29]
	s_mov_b64 s[12:13], 0x200
	v_lshl_add_u64 v[36:37], v[2:3], 0, s[12:13]
	v_mov_b32_e32 v2, 0
	s_mov_b32 s12, -4
	v_mov_b32_e32 v3, v2
	v_mov_b32_e32 v4, v2
	v_mov_b32_e32 v5, v2
	v_mov_b32_e32 v6, v2
	v_mov_b32_e32 v7, v2
	v_mov_b32_e32 v8, v2
	v_mov_b32_e32 v9, v2
	v_mov_b32_e32 v10, v2
	v_mov_b32_e32 v11, v2
	v_mov_b32_e32 v12, v2
	v_mov_b32_e32 v13, v2
	v_mov_b32_e32 v14, v2
	v_mov_b32_e32 v15, v2
	v_mov_b32_e32 v16, v2
	v_mov_b32_e32 v17, v2
	v_mov_b32_e32 v18, v2
	v_mov_b32_e32 v19, v2
	v_mov_b32_e32 v20, v2
	v_mov_b32_e32 v21, v2
	v_mov_b32_e32 v22, v2
	v_mov_b32_e32 v23, v2
	v_mov_b32_e32 v24, v2
	v_mov_b32_e32 v25, v2
	v_mov_b32_e32 v26, v2
	v_mov_b32_e32 v27, v2
	v_mov_b32_e32 v30, v2
	v_mov_b32_e32 v31, v2
	v_mov_b32_e32 v32, v2
	v_mov_b32_e32 v33, v2
	v_mov_b32_e32 v34, v2
	v_mov_b32_e32 v35, v2
	s_waitcnt lgkmcnt(0)
	s_barrier
	global_load_dword v40, v[36:37], off offset:-512
	global_load_dword v42, v[36:37], off offset:-256
	global_load_dword v38, v[36:37], off
	global_load_dword v0, v[36:37], off offset:256
	s_mov_b64 s[14:15], 0x400
	v_lshl_add_u64 v[36:37], v[36:37], 0, s[14:15]
	ds_read_b128 v[44:47], v39
	ds_read_b128 v[48:51], v39 offset:528
	s_waitcnt vmcnt(0)
; DI void compress_item(const Params& p, int l, int item, char* lds) {
;     ...
;     for (int n = 0; n < 128; n += 4) {
;       const float w0 = w2[n * 64 + e], w1v = w2[(n + 1) * 64 + e], w2v = w2[(n + 2) * 64 + e], w3 = w2[(n + 3) * 64 + e];
; #pragma unroll
;       for (int i = 0; i < 32; ++i) {
;         const float4 hv = *(const float4*)(hid + (rq * 32 + i) * 132 + n);
;         o[i] += hv.x * w0 + hv.y * w1v + hv.z * w2v + hv.w * w3;
;       }
;     }
.LBB0_428:
	s_add_i32 s12, s12, 4
	s_cmpk_gt_u32 s12, 0x7b
	s_cbranch_scc1 .Lmlp2_nopf
	global_load_dword v228, v[36:37], off offset:-512
	global_load_dword v229, v[36:37], off offset:-256
	global_load_dword v230, v[36:37], off
	global_load_dword v231, v[36:37], off offset:256
	v_lshl_add_u64 v[36:37], v[36:37], 0, s[14:15]
.Lmlp2_nopf:
	ds_read_b128 v[232:235], v39 offset:1056
	ds_read_b128 v[236:239], v39 offset:1584
	s_waitcnt lgkmcnt(2)
	v_mov_b32_e32 v53, v44
	v_mov_b32_e32 v44, v49
	v_mov_b32_e32 v52, v48
	v_pk_mul_f32 v[44:45], v[42:43], v[44:45] op_sel_hi:[0,1]
	v_pk_fma_f32 v[44:45], v[40:41], v[52:53], v[44:45] op_sel_hi:[0,1,1]
	v_mov_b32_e32 v48, v50
	v_mov_b32_e32 v49, v46
	v_pk_fma_f32 v[44:45], v[38:39], v[48:49], v[44:45] op_sel_hi:[0,1,1]
	v_mov_b32_e32 v46, v51
	v_pk_fma_f32 v[44:45], v[0:1], v[46:47], v[44:45] op_sel_hi:[0,1,1]
	v_pk_add_f32 v[34:35], v[34:35], v[44:45]
	ds_read_b128 v[44:47], v39 offset:2112
	ds_read_b128 v[48:51], v39 offset:2640
	s_waitcnt lgkmcnt(2)
	v_mov_b32_e32 v241, v232
	v_mov_b32_e32 v232, v237
	v_mov_b32_e32 v240, v236
	v_pk_mul_f32 v[232:233], v[42:43], v[232:233] op_sel_hi:[0,1]
	v_pk_fma_f32 v[232:233], v[40:41], v[240:241], v[232:233] op_sel_hi:[0,1,1]
	v_mov_b32_e32 v236, v238
	v_mov_b32_e32 v237, v234
	v_pk_fma_f32 v[232:233], v[38:39], v[236:237], v[232:233] op_sel_hi:[0,1,1]
	v_mov_b32_e32 v234, v239
	v_pk_fma_f32 v[232:233], v[0:1], v[234:235], v[232:233] op_sel_hi:[0,1,1]
	v_pk_add_f32 v[32:33], v[32:33], v[232:233]
	ds_read_b128 v[232:235], v39 offset:3168
	ds_read_b128 v[236:239], v39 offset:3696
	s_waitcnt lgkmcnt(2)
	v_mov_b32_e32 v53, v44
	v_mov_b32_e32 v44, v49
	v_mov_b32_e32 v52, v48
	v_pk_mul_f32 v[44:45], v[42:43], v[44:45] op_sel_hi:[0,1]
	v_pk_fma_f32 v[44:45], v[40:41], v[52:53], v[44:45] op_sel_hi:[0,1,1]
	v_mov_b32_e32 v48, v50
	v_mov_b32_e32 v49, v46
	v_pk_fma_f32 v[44:45], v[38:39], v[48:49], v[44:45] op_sel_hi:[0,1,1]
	v_mov_b32_e32 v46, v51
	v_pk_fma_f32 v[44:45], v[0:1], v[46:47], v[44:45] op_sel_hi:[0,1,1]
	v_pk_add_f32 v[30:31], v[30:31], v[44:45]
	ds_read_b128 v[44:47], v39 offset:4224
	ds_read_b128 v[48:51], v39 offset:4752
	s_waitcnt lgkmcnt(2)
	v_mov_b32_e32 v241, v232
	v_mov_b32_e32 v232, v237
	v_mov_b32_e32 v240, v236
	v_pk_mul_f32 v[232:233], v[42:43], v[232:233] op_sel_hi:[0,1]
	v_pk_fma_f32 v[232:233], v[40:41], v[240:241], v[232:233] op_sel_hi:[0,1,1]
	v_mov_b32_e32 v236, v238
	v_mov_b32_e32 v237, v234
	v_pk_fma_f32 v[232:233], v[38:39], v[236:237], v[232:233] op_sel_hi:[0,1,1]
	v_mov_b32_e32 v234, v239
	v_pk_fma_f32 v[232:233], v[0:1], v[234:235], v[232:233] op_sel_hi:[0,1,1]
	v_pk_add_f32 v[26:27], v[26:27], v[232:233]
	ds_read_b128 v[232:235], v39 offset:5280
	ds_read_b128 v[236:239], v39 offset:5808
	s_waitcnt lgkmcnt(2)
	v_mov_b32_e32 v53, v44
	v_mov_b32_e32 v44, v49
	v_mov_b32_e32 v52, v48
	v_pk_mul_f32 v[44:45], v[42:43], v[44:45] op_sel_hi:[0,1]
	v_pk_fma_f32 v[44:45], v[40:41], v[52:53], v[44:45] op_sel_hi:[0,1,1]
	v_mov_b32_e32 v48, v50
	v_mov_b32_e32 v49, v46
	v_pk_fma_f32 v[44:45], v[38:39], v[48:49], v[44:45] op_sel_hi:[0,1,1]
	v_mov_b32_e32 v46, v51
	v_pk_fma_f32 v[44:45], v[0:1], v[46:47], v[44:45] op_sel_hi:[0,1,1]
	v_pk_add_f32 v[24:25], v[24:25], v[44:45]
	ds_read_b128 v[44:47], v39 offset:6336
	ds_read_b128 v[48:51], v39 offset:6864
	s_waitcnt lgkmcnt(2)
	v_mov_b32_e32 v241, v232
	v_mov_b32_e32 v232, v237
	v_mov_b32_e32 v240, v236
	v_pk_mul_f32 v[232:233], v[42:43], v[232:233] op_sel_hi:[0,1]
	v_pk_fma_f32 v[232:233], v[40:41], v[240:241], v[232:233] op_sel_hi:[0,1,1]
	v_mov_b32_e32 v236, v238
	v_mov_b32_e32 v237, v234
	v_pk_fma_f32 v[232:233], v[38:39], v[236:237], v[232:233] op_sel_hi:[0,1,1]
	v_mov_b32_e32 v234, v239
	v_pk_fma_f32 v[232:233], v[0:1], v[234:235], v[232:233] op_sel_hi:[0,1,1]
	v_pk_add_f32 v[22:23], v[22:23], v[232:233]
	ds_read_b128 v[232:235], v39 offset:7392
	ds_read_b128 v[236:239], v39 offset:7920
	s_waitcnt lgkmcnt(2)
	v_mov_b32_e32 v53, v44
	v_mov_b32_e32 v44, v49
	v_mov_b32_e32 v52, v48
	v_pk_mul_f32 v[44:45], v[42:43], v[44:45] op_sel_hi:[0,1]
	v_pk_fma_f32 v[44:45], v[40:41], v[52:53], v[44:45] op_sel_hi:[0,1,1]
	v_mov_b32_e32 v48, v50
	v_mov_b32_e32 v49, v46
	v_pk_fma_f32 v[44:45], v[38:39], v[48:49], v[44:45] op_sel_hi:[0,1,1]
	v_mov_b32_e32 v46, v51
	v_pk_fma_f32 v[44:45], v[0:1], v[46:47], v[44:45] op_sel_hi:[0,1,1]
	v_pk_add_f32 v[20:21], v[20:21], v[44:45]
	ds_read_b128 v[44:47], v39 offset:8448
	ds_read_b128 v[48:51], v39 offset:8976
	s_waitcnt lgkmcnt(2)
	v_mov_b32_e32 v241, v232
	v_mov_b32_e32 v232, v237
	v_mov_b32_e32 v240, v236
	v_pk_mul_f32 v[232:233], v[42:43], v[232:233] op_sel_hi:[0,1]
	v_pk_fma_f32 v[232:233], v[40:41], v[240:241], v[232:233] op_sel_hi:[0,1,1]
	v_mov_b32_e32 v236, v238
	v_mov_b32_e32 v237, v234
	v_pk_fma_f32 v[232:233], v[38:39], v[236:237], v[232:233] op_sel_hi:[0,1,1]
	v_mov_b32_e32 v234, v239
	v_pk_fma_f32 v[232:233], v[0:1], v[234:235], v[232:233] op_sel_hi:[0,1,1]
	v_pk_add_f32 v[18:19], v[18:19], v[232:233]
	ds_read_b128 v[232:235], v39 offset:9504
	ds_read_b128 v[236:239], v39 offset:10032
	s_waitcnt lgkmcnt(2)
	v_mov_b32_e32 v53, v44
	v_mov_b32_e32 v44, v49
	v_mov_b32_e32 v52, v48
	v_pk_mul_f32 v[44:45], v[42:43], v[44:45] op_sel_hi:[0,1]
	v_pk_fma_f32 v[44:45], v[40:41], v[52:53], v[44:45] op_sel_hi:[0,1,1]
	v_mov_b32_e32 v48, v50
	v_mov_b32_e32 v49, v46
	v_pk_fma_f32 v[44:45], v[38:39], v[48:49], v[44:45] op_sel_hi:[0,1,1]
	v_mov_b32_e32 v46, v51
	v_pk_fma_f32 v[44:45], v[0:1], v[46:47], v[44:45] op_sel_hi:[0,1,1]
	v_pk_add_f32 v[16:17], v[16:17], v[44:45]
	ds_read_b128 v[44:47], v39 offset:10560
	ds_read_b128 v[48:51], v39 offset:11088
	s_waitcnt lgkmcnt(2)
; DI void compress_item(const Params& p, int l, int item, char* lds) {
;     ...
;     for (int n = 0; n < 128; n += 4) {
;       const float w0 = w2[n * 64 + e], w1v = w2[(n + 1) * 64 + e], w2v = w2[(n + 2) * 64 + e], w3 = w2[(n + 3) * 64 + e];
; #pragma unroll
;       for (int i = 0; i < 32; ++i) {
;         const float4 hv = *(const float4*)(hid + (rq * 32 + i) * 132 + n);
;         o[i] += hv.x * w0 + hv.y * w1v + hv.z * w2v + hv.w * w3;
;       }
;     }
;     const float gk = p.kn_c[l * 64 + e];
; #pragma unroll
;     for (int i = 0; i < 32; ++i) {
;       const int c = half * 128 + rq * 32 + i;
;       float v = o[i];
;       if (kv == 0) {
;         const float ss = wave_sum(v * v, lane);
;         v = v * rsqrtf(ss * (1.f / 64.f) + 1e-6f) * gk;
	v_mov_b32_e32 v241, v232
	v_mov_b32_e32 v232, v237
	v_mov_b32_e32 v240, v236
	v_pk_mul_f32 v[232:233], v[42:43], v[232:233] op_sel_hi:[0,1]
	v_pk_fma_f32 v[232:233], v[40:41], v[240:241], v[232:233] op_sel_hi:[0,1,1]
	v_mov_b32_e32 v236, v238
	v_mov_b32_e32 v237, v234
	v_pk_fma_f32 v[232:233], v[38:39], v[236:237], v[232:233] op_sel_hi:[0,1,1]
	v_mov_b32_e32 v234, v239
	v_pk_fma_f32 v[232:233], v[0:1], v[234:235], v[232:233] op_sel_hi:[0,1,1]
	v_pk_add_f32 v[14:15], v[14:15], v[232:233]
	ds_read_b128 v[232:235], v39 offset:11616
	ds_read_b128 v[236:239], v39 offset:12144
	s_waitcnt lgkmcnt(2)
	v_mov_b32_e32 v53, v44
	v_mov_b32_e32 v44, v49
	v_mov_b32_e32 v52, v48
	v_pk_mul_f32 v[44:45], v[42:43], v[44:45] op_sel_hi:[0,1]
	v_pk_fma_f32 v[44:45], v[40:41], v[52:53], v[44:45] op_sel_hi:[0,1,1]
	v_mov_b32_e32 v48, v50
	v_mov_b32_e32 v49, v46
	v_pk_fma_f32 v[44:45], v[38:39], v[48:49], v[44:45] op_sel_hi:[0,1,1]
	v_mov_b32_e32 v46, v51
	v_pk_fma_f32 v[44:45], v[0:1], v[46:47], v[44:45] op_sel_hi:[0,1,1]
	v_pk_add_f32 v[12:13], v[12:13], v[44:45]
	ds_read_b128 v[44:47], v39 offset:12672
	ds_read_b128 v[48:51], v39 offset:13200
	s_waitcnt lgkmcnt(2)
	v_mov_b32_e32 v241, v232
	v_mov_b32_e32 v232, v237
	v_mov_b32_e32 v240, v236
	v_pk_mul_f32 v[232:233], v[42:43], v[232:233] op_sel_hi:[0,1]
	v_pk_fma_f32 v[232:233], v[40:41], v[240:241], v[232:233] op_sel_hi:[0,1,1]
	v_mov_b32_e32 v236, v238
	v_mov_b32_e32 v237, v234
	v_pk_fma_f32 v[232:233], v[38:39], v[236:237], v[232:233] op_sel_hi:[0,1,1]
	v_mov_b32_e32 v234, v239
	v_pk_fma_f32 v[232:233], v[0:1], v[234:235], v[232:233] op_sel_hi:[0,1,1]
	v_pk_add_f32 v[10:11], v[10:11], v[232:233]
	ds_read_b128 v[232:235], v39 offset:13728
	ds_read_b128 v[236:239], v39 offset:14256
	s_waitcnt lgkmcnt(2)
	v_mov_b32_e32 v53, v44
	v_mov_b32_e32 v44, v49
	v_mov_b32_e32 v52, v48
	v_pk_mul_f32 v[44:45], v[42:43], v[44:45] op_sel_hi:[0,1]
	v_pk_fma_f32 v[44:45], v[40:41], v[52:53], v[44:45] op_sel_hi:[0,1,1]
	v_mov_b32_e32 v48, v50
	v_mov_b32_e32 v49, v46
	v_pk_fma_f32 v[44:45], v[38:39], v[48:49], v[44:45] op_sel_hi:[0,1,1]
	v_mov_b32_e32 v46, v51
	v_pk_fma_f32 v[44:45], v[0:1], v[46:47], v[44:45] op_sel_hi:[0,1,1]
	v_pk_add_f32 v[8:9], v[8:9], v[44:45]
	ds_read_b128 v[44:47], v39 offset:14784
	ds_read_b128 v[48:51], v39 offset:15312
	s_waitcnt lgkmcnt(2)
	v_mov_b32_e32 v241, v232
	v_mov_b32_e32 v232, v237
	v_mov_b32_e32 v240, v236
	v_pk_mul_f32 v[232:233], v[42:43], v[232:233] op_sel_hi:[0,1]
	v_pk_fma_f32 v[232:233], v[40:41], v[240:241], v[232:233] op_sel_hi:[0,1,1]
	v_mov_b32_e32 v236, v238
	v_mov_b32_e32 v237, v234
	v_pk_fma_f32 v[232:233], v[38:39], v[236:237], v[232:233] op_sel_hi:[0,1,1]
	v_mov_b32_e32 v234, v239
	v_pk_fma_f32 v[232:233], v[0:1], v[234:235], v[232:233] op_sel_hi:[0,1,1]
	v_pk_add_f32 v[6:7], v[6:7], v[232:233]
	ds_read_b128 v[232:235], v39 offset:15840
	ds_read_b128 v[236:239], v39 offset:16368
	s_waitcnt lgkmcnt(2)
	v_mov_b32_e32 v53, v44
	v_mov_b32_e32 v44, v49
	v_mov_b32_e32 v52, v48
	v_pk_mul_f32 v[44:45], v[42:43], v[44:45] op_sel_hi:[0,1]
	v_pk_fma_f32 v[44:45], v[40:41], v[52:53], v[44:45] op_sel_hi:[0,1,1]
	v_mov_b32_e32 v48, v50
	v_mov_b32_e32 v49, v46
	v_pk_fma_f32 v[44:45], v[38:39], v[48:49], v[44:45] op_sel_hi:[0,1,1]
	v_mov_b32_e32 v46, v51
	v_pk_fma_f32 v[44:45], v[0:1], v[46:47], v[44:45] op_sel_hi:[0,1,1]
	v_pk_add_f32 v[4:5], v[4:5], v[44:45]
	v_add_u32_e32 v39, 16, v39
	s_nop 0
	ds_read_b128 v[44:47], v39
	ds_read_b128 v[48:51], v39 offset:528
	s_waitcnt lgkmcnt(2)
	v_mov_b32_e32 v241, v232
	v_mov_b32_e32 v232, v237
	v_mov_b32_e32 v240, v236
	v_pk_mul_f32 v[232:233], v[42:43], v[232:233] op_sel_hi:[0,1]
	v_pk_fma_f32 v[232:233], v[40:41], v[240:241], v[232:233] op_sel_hi:[0,1,1]
	v_mov_b32_e32 v236, v238
	v_mov_b32_e32 v237, v234
	v_pk_fma_f32 v[232:233], v[38:39], v[236:237], v[232:233] op_sel_hi:[0,1,1]
	v_mov_b32_e32 v234, v239
	v_pk_fma_f32 v[232:233], v[0:1], v[234:235], v[232:233] op_sel_hi:[0,1,1]
	v_pk_add_f32 v[2:3], v[2:3], v[232:233]
	s_cbranch_scc1 .Lmlp2_exit
	s_waitcnt vmcnt(0)
	v_mov_b32_e32 v40, v228
	v_mov_b32_e32 v42, v229
	v_mov_b32_e32 v38, v230
	v_mov_b32_e32 v0, v231
	s_branch .LBB0_428
.Lmlp2_exit:
	s_waitcnt lgkmcnt(0)
	v_or_b32_e32 v0, s2, v43
	v_lshl_add_u64 v[36:37], v[0:1], 2, s[72:73]
	global_load_dword v36, v[36:37], off
	v_readlane_b32 s80, v251, 34
	v_readlane_b32 s88, v251, 42
	v_readlane_b32 s89, v251, 43
	v_xor_b32_e32 v42, 0x80, v28
	v_xor_b32_e32 v41, 64, v28
	v_xor_b32_e32 v40, 32, v28
	v_xor_b32_e32 v39, 16, v28
	v_xor_b32_e32 v38, 8, v28
	v_xor_b32_e32 v37, 4, v28
	s_and_b64 vcc, s[0:1], exec
	v_readlane_b32 s86, v251, 40
	v_readlane_b32 s87, v251, 41
	s_mov_b64 s[12:13], s[88:89]
	v_readlane_b32 s81, v251, 35
	v_readlane_b32 s82, v251, 36
	v_readlane_b32 s83, v251, 37
	v_readlane_b32 s84, v251, 38
	v_readlane_b32 s85, v251, 39
	v_readlane_b32 s90, v251, 44
	v_readlane_b32 s91, v251, 45
	v_readlane_b32 s92, v251, 46
	v_readlane_b32 s93, v251, 47
	v_readlane_b32 s94, v251, 48
	v_readlane_b32 s95, v251, 49
	s_cbranch_vccz .LBB0_431
	v_mul_f32_e32 v0, v35, v35
	ds_bpermute_b32 v0, v42, v0
	s_mov_b64 s[12:13], s[86:87]
	s_waitcnt lgkmcnt(0)
	v_fmac_f32_e32 v0, v35, v35
	ds_bpermute_b32 v28, v41, v0
	s_waitcnt lgkmcnt(0)
	v_add_f32_e32 v0, v0, v28
	ds_bpermute_b32 v28, v40, v0
	s_waitcnt lgkmcnt(0)
	v_add_f32_e32 v0, v0, v28
	ds_bpermute_b32 v28, v39, v0
	s_waitcnt lgkmcnt(0)
	v_add_f32_e32 v0, v0, v28
	ds_bpermute_b32 v28, v38, v0
	s_waitcnt lgkmcnt(0)
	v_add_f32_e32 v0, v0, v28
	ds_bpermute_b32 v28, v37, v0
	s_waitcnt lgkmcnt(0)
	v_add_f32_e32 v0, v0, v28
	v_fmamk_f32 v0, v0, 0x3c800000, v222
	v_mul_f32_e32 v28, 0x4b800000, v0
	v_cmp_gt_f32_e32 vcc, s56, v0
	s_nop 1
	v_cndmask_b32_e32 v0, v0, v28, vcc
	v_rsq_f32_e32 v0, v0
	s_nop 0
	v_mul_f32_e32 v28, 0x45800000, v0
	v_cndmask_b32_e32 v0, v0, v28, vcc
	v_mul_f32_e32 v0, v35, v0
	s_waitcnt vmcnt(0)
	v_mul_f32_e32 v35, v36, v0
